# fp16 K-loop: loop-carried operand selection and counter updates sunk below the first segment's LDS reads and staging loads (loop-back path is tail + two address adds)
# baseline (speedup 1.0000x reference)
; #define PG8_STAGE(bufoff, gbase, voff, h64) do { \
;         __builtin_amdgcn_global_load_lds((const unsigned*)((const char*)(gbase) + (voff)), (LAS unsigned*)(lds + (bufoff) + ldsw), 16, 0, 0); \
;         __builtin_amdgcn_global_load_lds((const unsigned*)((const char*)(gbase) + (h64) + (voff)), (LAS unsigned*)(lds + (bufoff) + ldsw + 8192), 16, 0, 0); } while (0)
; #define PG8_LDA(dst, b, h) do { _Pragma("unroll") for (int m = 0; m < 4; ++m) { dst[m].lo = *(const LAS f16x8*)(lds + PG8_SA(b, h) + aoff + m * 2048); dst[m].hi = *(const LAS f16x8*)(lds + PG8_SA(b, h) + aoff + m * 2048 + 1024); } } while (0)
; #define PG8_LDB(dst, b, h) do { _Pragma("unroll") for (int n = 0; n < 2; ++n) { dst[n].lo = *(const LAS f16x8*)(lds + PG8_SB(b, h) + boff + n * 2048); dst[n].hi = *(const LAS f16x8*)(lds + PG8_SB(b, h) + boff + n * 2048 + 1024); } } while (0)
; #define PG8_WAIT_V(n) asm volatile("s_waitcnt vmcnt(" #n ")" ::: "memory")
; #define PG8_WAIT_L(n) asm volatile("s_waitcnt lgkmcnt(" #n ")" ::: "memory")
; #define PG8_BAR __builtin_amdgcn_s_barrier()
; #define PG8_SCHED __builtin_amdgcn_sched_barrier(0)
; template <bool F8 = false, class Sched, class Epi>
; __device__ __forceinline__ void gemm_phase(LAS unsigned char* lds, const Sched& S, const Epi& E) {
;     ...
;         for (int t = 0; t < nt; t += 2) {
;             const bool last = (t == nt - 2);
;             const char* a1 = cA + (size_t)(t + 1) * kstep;
;             const char* a2 = last ? nA : cA + (size_t)(t + 2) * kstep; const char* b2 = last ? nB : cB + (size_t)(t + 2) * kstep;
;             const char* a3 = a2 + kstep; const char* b3 = b2 + kstep;
;             const unsigned vA2 = last ? nvA : cvA, vB2 = last ? nvB : cvB;
;             const size_t h2 = last ? nh64 : ch64, hs2 = last ? nhs : chs, bhs2 = last ? nbhs : cbhs;
;             PG8_LDB(B0, 0, 0); PG8_LDB(B1, 0, 1); PG8_SCHED; PG8_LDA(At, 0, 0); PG8_STAGE(PG8_SA(1, 1), a1 + chs, cvA, ch64);
;             PG8_WAIT_V(8); PG8_WAIT_L(0); PG8_BAR; PG8_MMA(0, 0, At, B0); PG8_MMA(0, 1, At, B1); PG8_BAR; PG8_SCHED;
;             PG8_LDA(At, 0, 1); PG8_STAGE(PG8_SB(0, 0), b2, vB2, h2); PG8_STAGE(PG8_SB(0, 1), b2 + bhs2, vB2, h2); PG8_STAGE(PG8_SA(0, 0), a2, vA2, h2);
;             PG8_WAIT_V(8); PG8_WAIT_L(0); PG8_BAR; PG8_MMA(1, 0, At, B0); PG8_MMA(1, 1, At, B1); PG8_BAR; PG8_SCHED;
.LBB0_214:
	v_add_u32_e32 v150, 0x10000, v187
	v_add_u32_e32 v166, 0x14000, v187
	ds_read_b128 v[138:141], v150
	ds_read_b128 v[142:145], v150 offset:1024
	ds_read_b128 v[146:149], v150 offset:2048
	ds_read_b128 v[150:153], v150 offset:3072
	ds_read_b128 v[154:157], v166
	ds_read_b128 v[158:161], v166 offset:1024
	ds_read_b128 v[162:165], v166 offset:2048
	ds_read_b128 v[166:169], v166 offset:3072
	v_lshl_add_u64 v[182:183], v[132:133], 0, s[10:11]
	s_add_i32 m0, s71, 0xc000
	ds_read_b128 v[170:173], v202
	ds_read_b128 v[174:177], v202 offset:1024
	ds_read_b128 v[178:181], v202 offset:2048
	ds_read_b128 v[190:193], v202 offset:3072
	ds_read_b128 v[198:201], v202 offset:4096
	ds_read_b128 v[204:207], v202 offset:5120
	ds_read_b128 v[208:211], v202 offset:6144
	ds_read_b128 v[212:215], v202 offset:7168
	global_load_lds_dwordx4 v[182:183], off
	v_lshl_add_u64 v[182:183], v[134:135], 0, s[10:11]
	s_add_i32 m0, s71, 0xe000
	s_nop 0
	global_load_lds_dwordx4 v[182:183], off
	s_cmp_eq_u32 s68, s79
	s_cselect_b64 s[86:87], -1, 0
	s_and_b64 vcc, exec, s[86:87]
	v_mov_b64_e32 v[136:137], v[34:35]
	s_mov_b64 s[8:9], s[80:81]
	s_mov_b64 s[84:85], s[18:19]
	s_mov_b64 s[12:13], s[16:17]
	v_mov_b32_e32 v32, v188
	s_mov_b64 s[6:7], s[72:73]
	s_cbranch_vccnz .Lk16_sel
	s_add_u32 s6, s69, s10
	s_addc_u32 s7, s78, s11
	v_mov_b64_e32 v[136:137], v[184:185]
	s_mov_b64 s[8:9], s[66:67]
	s_mov_b64 s[84:85], s[90:91]
	s_mov_b64 s[12:13], s[88:89]
	v_mov_b32_e32 v32, v186
.Lk16_sel:
	s_add_i32 s79, s79, 2
	s_add_u32 vcc_lo, s14, s10
	s_addc_u32 vcc_hi, s15, s11
	s_add_u32 vcc_lo, vcc_lo, 0x100
	s_addc_u32 vcc_hi, vcc_hi, 0
	s_and_b64 s[86:87], exec, s[86:87]
	s_cselect_b32 vcc_hi, s29, vcc_hi
	s_cselect_b32 vcc_lo, s96, vcc_lo
	s_add_i32 s86, 0, 0x10000
	s_add_i32 s45, 0, 0x14000
	s_waitcnt vmcnt(8)
	s_waitcnt lgkmcnt(0)
	s_setprio 1
	s_barrier
	v_mfma_f32_16x16x32_f16 v[128:131], v[138:141], v[170:173], v[128:131]
	v_mfma_f32_16x16x32_f16 v[124:127], v[146:149], v[170:173], v[124:127]
	v_mfma_f32_16x16x32_f16 v[112:115], v[138:141], v[178:181], v[112:115]
	v_mfma_f32_16x16x32_f16 v[108:111], v[146:149], v[178:181], v[108:111]
	v_mfma_f32_16x16x32_f16 v[96:99], v[138:141], v[198:201], v[96:99]
	v_mfma_f32_16x16x32_f16 v[92:95], v[146:149], v[198:201], v[92:95]
	v_mfma_f32_16x16x32_f16 v[80:83], v[138:141], v[208:211], v[80:83]
	v_mfma_f32_16x16x32_f16 v[76:79], v[146:149], v[208:211], v[76:79]
	v_mfma_f32_16x16x32_f16 v[128:131], v[142:145], v[174:177], v[128:131]
	v_mfma_f32_16x16x32_f16 v[124:127], v[150:153], v[174:177], v[124:127]
	v_mfma_f32_16x16x32_f16 v[112:115], v[142:145], v[190:193], v[112:115]
	v_mfma_f32_16x16x32_f16 v[108:111], v[150:153], v[190:193], v[108:111]
	v_mfma_f32_16x16x32_f16 v[96:99], v[142:145], v[204:207], v[96:99]
	v_mfma_f32_16x16x32_f16 v[92:95], v[150:153], v[204:207], v[92:95]
	v_mfma_f32_16x16x32_f16 v[80:83], v[142:145], v[212:215], v[80:83]
	v_mfma_f32_16x16x32_f16 v[76:79], v[150:153], v[212:215], v[76:79]
	v_mfma_f32_16x16x32_f16 v[120:123], v[154:157], v[170:173], v[120:123]
	v_mfma_f32_16x16x32_f16 v[116:119], v[162:165], v[170:173], v[116:119]
	v_mfma_f32_16x16x32_f16 v[104:107], v[154:157], v[178:181], v[104:107]
	v_mfma_f32_16x16x32_f16 v[100:103], v[162:165], v[178:181], v[100:103]
	v_mfma_f32_16x16x32_f16 v[88:91], v[154:157], v[198:201], v[88:91]
	v_mfma_f32_16x16x32_f16 v[84:87], v[162:165], v[198:201], v[84:87]
	v_mfma_f32_16x16x32_f16 v[72:75], v[154:157], v[208:211], v[72:75]
	v_mfma_f32_16x16x32_f16 v[68:71], v[162:165], v[208:211], v[68:71]
	v_mfma_f32_16x16x32_f16 v[120:123], v[158:161], v[174:177], v[120:123]
	v_mfma_f32_16x16x32_f16 v[116:119], v[166:169], v[174:177], v[116:119]
	v_mfma_f32_16x16x32_f16 v[104:107], v[158:161], v[190:193], v[104:107]
	v_mfma_f32_16x16x32_f16 v[100:103], v[166:169], v[190:193], v[100:103]
	v_mfma_f32_16x16x32_f16 v[88:91], v[158:161], v[204:207], v[88:91]
	v_mfma_f32_16x16x32_f16 v[84:87], v[166:169], v[204:207], v[84:87]
	v_mfma_f32_16x16x32_f16 v[72:75], v[158:161], v[212:215], v[72:75]
	v_mfma_f32_16x16x32_f16 v[68:71], v[166:169], v[212:215], v[68:71]
	s_barrier
	s_setprio 0
	s_add_i32 s65, s86, s49
	s_mov_b32 m0, s65
	s_add_u32 s86, s6, s12
	ds_read_b128 v[170:173], v202 offset:16384
	ds_read_b128 v[174:177], v202 offset:17408
	ds_read_b128 v[178:181], v202 offset:18432
	ds_read_b128 v[190:193], v202 offset:19456
	ds_read_b128 v[198:201], v202 offset:20480
	ds_read_b128 v[204:207], v202 offset:21504
	ds_read_b128 v[208:211], v202 offset:22528
	ds_read_b128 v[212:215], v202 offset:23552
	global_load_lds_dwordx4 v32, s[6:7]
	s_addc_u32 s87, s7, s13
	s_add_i32 m0, s65, 0x2000
	v_lshl_add_u64 v[182:183], s[6:7], 0, v[32:33]
	s_add_u32 s6, s6, s8
	s_addc_u32 s7, s7, s9
	s_add_i32 s8, s45, s49
	global_load_lds_dwordx4 v32, s[86:87]
	s_mov_b32 m0, s8
	v_lshl_add_u64 v[216:217], s[6:7], 0, v[32:33]
	global_load_lds_dwordx4 v32, s[6:7]
	s_add_u32 s6, s6, s12
	s_addc_u32 s7, s7, s13
	s_add_i32 m0, s8, 0x2000
	v_lshl_add_u64 v[234:235], s[6:7], 0, v[32:33]
	global_load_lds_dwordx4 v32, s[6:7]
	s_add_u32 s6, vcc_lo, s12
	v_lshl_add_u64 v[236:237], vcc, 0, v[136:137]
	s_mov_b32 m0, s71
	s_addc_u32 s7, vcc_hi, s13
	global_load_lds_dwordx4 v[236:237], off
	v_lshl_add_u64 v[238:239], s[6:7], 0, v[136:137]
	s_mov_b32 m0, s82
	v_lshl_add_u64 v[194:195], s[86:87], 0, v[32:33]
	global_load_lds_dwordx4 v[238:239], off
	s_waitcnt vmcnt(8)
	s_waitcnt lgkmcnt(0)
	s_setprio 1
	s_barrier
; #define PG8_STAGE(bufoff, gbase, voff, h64) do { \
;         __builtin_amdgcn_global_load_lds((const unsigned*)((const char*)(gbase) + (voff)), (LAS unsigned*)(lds + (bufoff) + ldsw), 16, 0, 0); \
;         __builtin_amdgcn_global_load_lds((const unsigned*)((const char*)(gbase) + (h64) + (voff)), (LAS unsigned*)(lds + (bufoff) + ldsw + 8192), 16, 0, 0); } while (0)
; #define PG8_LDA(dst, b, h) do { _Pragma("unroll") for (int m = 0; m < 4; ++m) { dst[m].lo = *(const LAS f16x8*)(lds + PG8_SA(b, h) + aoff + m * 2048); dst[m].hi = *(const LAS f16x8*)(lds + PG8_SA(b, h) + aoff + m * 2048 + 1024); } } while (0)
; #define PG8_LDB(dst, b, h) do { _Pragma("unroll") for (int n = 0; n < 2; ++n) { dst[n].lo = *(const LAS f16x8*)(lds + PG8_SB(b, h) + boff + n * 2048); dst[n].hi = *(const LAS f16x8*)(lds + PG8_SB(b, h) + boff + n * 2048 + 1024); } } while (0)
; #define PG8_WAIT_V(n) asm volatile("s_waitcnt vmcnt(" #n ")" ::: "memory")
; #define PG8_WAIT_L(n) asm volatile("s_waitcnt lgkmcnt(" #n ")" ::: "memory")
; #define PG8_BAR __builtin_amdgcn_s_barrier()
; #define PG8_SCHED __builtin_amdgcn_sched_barrier(0)
; template <bool F8 = false, class Sched, class Epi>
; __device__ __forceinline__ void gemm_phase(LAS unsigned char* lds, const Sched& S, const Epi& E) {
;     ...
;             PG8_WAIT_V(8); PG8_WAIT_L(0); PG8_BAR; PG8_MMA(1, 0, At, B0); PG8_MMA(1, 1, At, B1); PG8_BAR; PG8_SCHED;
;             PG8_LDB(B0, 1, 0); PG8_LDB(B1, 1, 1); PG8_SCHED; PG8_LDA(At, 1, 0); PG8_STAGE(PG8_SA(0, 1), a2 + hs2, vA2, h2);
;             PG8_WAIT_V(8); PG8_WAIT_L(0); PG8_BAR; PG8_MMA(0, 0, At, B0); PG8_MMA(0, 1, At, B1); PG8_BAR; PG8_SCHED;
	v_mfma_f32_16x16x32_f16 v[64:67], v[138:141], v[170:173], v[64:67]
	v_mfma_f32_16x16x32_f16 v[60:63], v[146:149], v[170:173], v[60:63]
	v_mfma_f32_16x16x32_f16 v[48:51], v[138:141], v[178:181], v[48:51]
	v_mfma_f32_16x16x32_f16 v[44:47], v[146:149], v[178:181], v[44:47]
	v_mfma_f32_16x16x32_f16 v[28:31], v[138:141], v[198:201], v[28:31]
	v_mfma_f32_16x16x32_f16 v[24:27], v[146:149], v[198:201], v[24:27]
	v_mfma_f32_16x16x32_f16 v[12:15], v[138:141], v[208:211], v[12:15]
	v_mfma_f32_16x16x32_f16 v[8:11], v[146:149], v[208:211], v[8:11]
	v_mfma_f32_16x16x32_f16 v[64:67], v[142:145], v[174:177], v[64:67]
	v_mfma_f32_16x16x32_f16 v[60:63], v[150:153], v[174:177], v[60:63]
	v_mfma_f32_16x16x32_f16 v[48:51], v[142:145], v[190:193], v[48:51]
	v_mfma_f32_16x16x32_f16 v[44:47], v[150:153], v[190:193], v[44:47]
	v_mfma_f32_16x16x32_f16 v[28:31], v[142:145], v[204:207], v[28:31]
	v_mfma_f32_16x16x32_f16 v[24:27], v[150:153], v[204:207], v[24:27]
	v_mfma_f32_16x16x32_f16 v[12:15], v[142:145], v[212:215], v[12:15]
	v_mfma_f32_16x16x32_f16 v[8:11], v[150:153], v[212:215], v[8:11]
	v_mfma_f32_16x16x32_f16 v[56:59], v[154:157], v[170:173], v[56:59]
	v_mfma_f32_16x16x32_f16 v[52:55], v[162:165], v[170:173], v[52:55]
	v_mfma_f32_16x16x32_f16 v[40:43], v[154:157], v[178:181], v[40:43]
	v_mfma_f32_16x16x32_f16 v[36:39], v[162:165], v[178:181], v[36:39]
	v_mfma_f32_16x16x32_f16 v[20:23], v[154:157], v[198:201], v[20:23]
	v_mfma_f32_16x16x32_f16 v[16:19], v[162:165], v[198:201], v[16:19]
	v_mfma_f32_16x16x32_f16 v[4:7], v[154:157], v[208:211], v[4:7]
	v_mfma_f32_16x16x32_f16 v[0:3], v[162:165], v[208:211], v[0:3]
	v_mfma_f32_16x16x32_f16 v[56:59], v[158:161], v[174:177], v[56:59]
	v_mfma_f32_16x16x32_f16 v[52:55], v[166:169], v[174:177], v[52:55]
	v_mfma_f32_16x16x32_f16 v[40:43], v[158:161], v[190:193], v[40:43]
	v_mfma_f32_16x16x32_f16 v[36:39], v[166:169], v[190:193], v[36:39]
	v_mfma_f32_16x16x32_f16 v[20:23], v[158:161], v[204:207], v[20:23]
	v_mfma_f32_16x16x32_f16 v[16:19], v[166:169], v[204:207], v[16:19]
	v_mfma_f32_16x16x32_f16 v[4:7], v[158:161], v[212:215], v[4:7]
	v_mfma_f32_16x16x32_f16 v[0:3], v[166:169], v[212:215], v[0:3]
	s_barrier
	s_setprio 0
	s_add_i32 s8, 0, 0x18000
	v_add_u32_e32 v32, s8, v187
	s_add_i32 s9, 0, 0x1c000
	ds_read_b128 v[138:141], v32
	ds_read_b128 v[142:145], v32 offset:1024
	ds_read_b128 v[146:149], v32 offset:2048
	ds_read_b128 v[150:153], v32 offset:3072
	v_add_u32_e32 v32, s9, v187
	ds_read_b128 v[154:157], v32
	ds_read_b128 v[158:161], v32 offset:1024
	ds_read_b128 v[162:165], v32 offset:2048
	ds_read_b128 v[166:169], v32 offset:3072
	s_add_u32 s6, vcc_lo, s84
	s_addc_u32 s7, vcc_hi, s85
	v_lshl_add_u64 v[240:241], s[6:7], 0, v[136:137]
	s_add_u32 s6, s6, s12
	s_mov_b32 m0, s83
	s_addc_u32 s7, s7, s13
	ds_read_b128 v[170:173], v202 offset:32768
	ds_read_b128 v[174:177], v202 offset:33792
	ds_read_b128 v[178:181], v202 offset:34816
	ds_read_b128 v[190:193], v202 offset:35840
	ds_read_b128 v[198:201], v202 offset:36864
	ds_read_b128 v[204:207], v202 offset:37888
	ds_read_b128 v[208:211], v202 offset:38912
	ds_read_b128 v[212:215], v202 offset:39936
	global_load_lds_dwordx4 v[240:241], off
	v_lshl_add_u64 v[136:137], s[6:7], 0, v[136:137]
	s_mov_b32 m0, s44
	s_nop 0
	global_load_lds_dwordx4 v[136:137], off
	s_waitcnt vmcnt(8)
	s_waitcnt lgkmcnt(0)
	s_setprio 1
	s_barrier
	v_mfma_f32_16x16x32_f16 v[128:131], v[138:141], v[170:173], v[128:131]
	v_mfma_f32_16x16x32_f16 v[124:127], v[146:149], v[170:173], v[124:127]
	v_mfma_f32_16x16x32_f16 v[112:115], v[138:141], v[178:181], v[112:115]
	v_mfma_f32_16x16x32_f16 v[108:111], v[146:149], v[178:181], v[108:111]
	v_mfma_f32_16x16x32_f16 v[96:99], v[138:141], v[198:201], v[96:99]
	v_mfma_f32_16x16x32_f16 v[92:95], v[146:149], v[198:201], v[92:95]
	v_mfma_f32_16x16x32_f16 v[80:83], v[138:141], v[208:211], v[80:83]
	v_mfma_f32_16x16x32_f16 v[76:79], v[146:149], v[208:211], v[76:79]
	v_mfma_f32_16x16x32_f16 v[128:131], v[142:145], v[174:177], v[128:131]
	v_mfma_f32_16x16x32_f16 v[124:127], v[150:153], v[174:177], v[124:127]
	v_mfma_f32_16x16x32_f16 v[112:115], v[142:145], v[190:193], v[112:115]
	v_mfma_f32_16x16x32_f16 v[108:111], v[150:153], v[190:193], v[108:111]
	v_mfma_f32_16x16x32_f16 v[96:99], v[142:145], v[204:207], v[96:99]
	v_mfma_f32_16x16x32_f16 v[92:95], v[150:153], v[204:207], v[92:95]
	v_mfma_f32_16x16x32_f16 v[80:83], v[142:145], v[212:215], v[80:83]
	v_mfma_f32_16x16x32_f16 v[76:79], v[150:153], v[212:215], v[76:79]
	v_mfma_f32_16x16x32_f16 v[120:123], v[154:157], v[170:173], v[120:123]
	v_mfma_f32_16x16x32_f16 v[116:119], v[162:165], v[170:173], v[116:119]
	v_mfma_f32_16x16x32_f16 v[104:107], v[154:157], v[178:181], v[104:107]
	v_mfma_f32_16x16x32_f16 v[100:103], v[162:165], v[178:181], v[100:103]
	v_mfma_f32_16x16x32_f16 v[88:91], v[154:157], v[198:201], v[88:91]
	v_mfma_f32_16x16x32_f16 v[84:87], v[162:165], v[198:201], v[84:87]
	v_mfma_f32_16x16x32_f16 v[72:75], v[154:157], v[208:211], v[72:75]
	v_mfma_f32_16x16x32_f16 v[68:71], v[162:165], v[208:211], v[68:71]
	v_mfma_f32_16x16x32_f16 v[120:123], v[158:161], v[174:177], v[120:123]
	v_mfma_f32_16x16x32_f16 v[116:119], v[166:169], v[174:177], v[116:119]
	v_mfma_f32_16x16x32_f16 v[104:107], v[158:161], v[190:193], v[104:107]
	v_mfma_f32_16x16x32_f16 v[100:103], v[166:169], v[190:193], v[100:103]
	v_mfma_f32_16x16x32_f16 v[88:91], v[158:161], v[204:207], v[88:91]
	v_mfma_f32_16x16x32_f16 v[84:87], v[166:169], v[204:207], v[84:87]
	v_mfma_f32_16x16x32_f16 v[72:75], v[158:161], v[212:215], v[72:75]
	v_mfma_f32_16x16x32_f16 v[68:71], v[166:169], v[212:215], v[68:71]
	s_barrier
; #define PG8_STAGE(bufoff, gbase, voff, h64) do { \
;         __builtin_amdgcn_global_load_lds((const unsigned*)((const char*)(gbase) + (voff)), (LAS unsigned*)(lds + (bufoff) + ldsw), 16, 0, 0); \
;         __builtin_amdgcn_global_load_lds((const unsigned*)((const char*)(gbase) + (h64) + (voff)), (LAS unsigned*)(lds + (bufoff) + ldsw + 8192), 16, 0, 0); } while (0)
; #define PG8_LDA(dst, b, h) do { _Pragma("unroll") for (int m = 0; m < 4; ++m) { dst[m].lo = *(const LAS f16x8*)(lds + PG8_SA(b, h) + aoff + m * 2048); dst[m].hi = *(const LAS f16x8*)(lds + PG8_SA(b, h) + aoff + m * 2048 + 1024); } } while (0)
; #define PG8_WAIT_V(n) asm volatile("s_waitcnt vmcnt(" #n ")" ::: "memory")
; #define PG8_WAIT_L(n) asm volatile("s_waitcnt lgkmcnt(" #n ")" ::: "memory")
; #define PG8_BAR __builtin_amdgcn_s_barrier()
; #define PG8_SCHED __builtin_amdgcn_sched_barrier(0)
; template <bool F8 = false, class Sched, class Epi>
; __device__ __forceinline__ void gemm_phase(LAS unsigned char* lds, const Sched& S, const Epi& E) {
;     ...
;             PG8_LDA(At, 1, 1); PG8_STAGE(PG8_SB(1, 0), b3, vB2, h2); PG8_STAGE(PG8_SB(1, 1), b3 + bhs2, vB2, h2); PG8_STAGE(PG8_SA(1, 0), a3, vA2, h2);
;             PG8_WAIT_V(8); PG8_WAIT_L(0); PG8_BAR; PG8_MMA(1, 0, At, B0); PG8_MMA(1, 1, At, B1); PG8_BAR; PG8_SCHED;
;         }
;         if (wr == 0) PG8_BAR;
	s_setprio 0
	s_add_i32 s6, s8, s49
	v_lshl_add_u64 v[136:137], v[182:183], 0, s[40:41]
	s_mov_b32 m0, s6
	ds_read_b128 v[170:173], v202 offset:49152
	ds_read_b128 v[174:177], v202 offset:50176
	ds_read_b128 v[178:181], v202 offset:51200
	ds_read_b128 v[190:193], v202 offset:52224
	ds_read_b128 v[198:201], v202 offset:53248
	ds_read_b128 v[204:207], v202 offset:54272
	ds_read_b128 v[208:211], v202 offset:55296
	ds_read_b128 v[212:215], v202 offset:56320
	global_load_lds_dwordx4 v[136:137], off
	v_lshl_add_u64 v[136:137], v[194:195], 0, s[40:41]
	s_add_i32 m0, s6, 0x2000
	s_add_i32 s6, s9, s49
	global_load_lds_dwordx4 v[136:137], off
	v_lshl_add_u64 v[136:137], v[216:217], 0, s[40:41]
	s_mov_b32 m0, s6
	s_nop 0
	global_load_lds_dwordx4 v[136:137], off
	v_lshl_add_u64 v[136:137], v[234:235], 0, s[40:41]
	s_add_i32 m0, s6, 0x2000
	s_nop 0
	global_load_lds_dwordx4 v[136:137], off
	v_lshl_add_u64 v[136:137], v[236:237], 0, s[40:41]
	s_mov_b32 m0, s92
	s_nop 0
	global_load_lds_dwordx4 v[136:137], off
	v_lshl_add_u64 v[136:137], v[238:239], 0, s[40:41]
	s_mov_b32 m0, s93
	s_nop 0
	global_load_lds_dwordx4 v[136:137], off
	s_waitcnt vmcnt(8)
	s_waitcnt lgkmcnt(0)
	s_setprio 1
	s_barrier
	v_mfma_f32_16x16x32_f16 v[64:67], v[138:141], v[170:173], v[64:67]
	v_mfma_f32_16x16x32_f16 v[60:63], v[146:149], v[170:173], v[60:63]
	v_mfma_f32_16x16x32_f16 v[48:51], v[138:141], v[178:181], v[48:51]
	v_mfma_f32_16x16x32_f16 v[44:47], v[146:149], v[178:181], v[44:47]
	v_mfma_f32_16x16x32_f16 v[28:31], v[138:141], v[198:201], v[28:31]
	v_mfma_f32_16x16x32_f16 v[24:27], v[146:149], v[198:201], v[24:27]
	v_mfma_f32_16x16x32_f16 v[12:15], v[138:141], v[208:211], v[12:15]
	v_mfma_f32_16x16x32_f16 v[8:11], v[146:149], v[208:211], v[8:11]
	v_mfma_f32_16x16x32_f16 v[64:67], v[142:145], v[174:177], v[64:67]
	v_mfma_f32_16x16x32_f16 v[60:63], v[150:153], v[174:177], v[60:63]
	v_mfma_f32_16x16x32_f16 v[48:51], v[142:145], v[190:193], v[48:51]
	v_mfma_f32_16x16x32_f16 v[44:47], v[150:153], v[190:193], v[44:47]
	v_mfma_f32_16x16x32_f16 v[28:31], v[142:145], v[204:207], v[28:31]
	v_mfma_f32_16x16x32_f16 v[24:27], v[150:153], v[204:207], v[24:27]
	v_mfma_f32_16x16x32_f16 v[12:15], v[142:145], v[212:215], v[12:15]
	v_mfma_f32_16x16x32_f16 v[8:11], v[150:153], v[212:215], v[8:11]
	v_mfma_f32_16x16x32_f16 v[56:59], v[154:157], v[170:173], v[56:59]
	v_mfma_f32_16x16x32_f16 v[52:55], v[162:165], v[170:173], v[52:55]
	v_mfma_f32_16x16x32_f16 v[40:43], v[154:157], v[178:181], v[40:43]
	v_mfma_f32_16x16x32_f16 v[36:39], v[162:165], v[178:181], v[36:39]
	v_mfma_f32_16x16x32_f16 v[20:23], v[154:157], v[198:201], v[20:23]
	v_mfma_f32_16x16x32_f16 v[16:19], v[162:165], v[198:201], v[16:19]
	v_mfma_f32_16x16x32_f16 v[4:7], v[154:157], v[208:211], v[4:7]
	v_mfma_f32_16x16x32_f16 v[0:3], v[162:165], v[208:211], v[0:3]
	v_mfma_f32_16x16x32_f16 v[56:59], v[158:161], v[174:177], v[56:59]
	v_mfma_f32_16x16x32_f16 v[52:55], v[166:169], v[174:177], v[52:55]
	v_mfma_f32_16x16x32_f16 v[40:43], v[158:161], v[190:193], v[40:43]
	v_mfma_f32_16x16x32_f16 v[36:39], v[166:169], v[190:193], v[36:39]
	v_mfma_f32_16x16x32_f16 v[20:23], v[158:161], v[204:207], v[20:23]
	v_mfma_f32_16x16x32_f16 v[16:19], v[166:169], v[204:207], v[16:19]
	v_mfma_f32_16x16x32_f16 v[4:7], v[158:161], v[212:215], v[4:7]
	v_mfma_f32_16x16x32_f16 v[0:3], v[166:169], v[212:215], v[0:3]
	s_barrier
	s_setprio 0
	s_add_u32 s10, s10, 0x100
	s_addc_u32 s11, s11, 0
	s_cmp_ge_u32 s79, s36
	s_cbranch_scc1 .LBB0_217
.LBB0_215:
	s_branch .LBB0_214
.LBB0_217:
	v_readlane_b32 s6, v251, 12
	v_readlane_b32 s7, v251, 13
	s_xor_b64 s[84:85], s[30:31], -1
	s_and_b64 vcc, exec, s[6:7]
	s_cbranch_vccz .LBB0_219
	s_barrier
